# grid barriers: XCD leader also issues its L1 invalidate early, beside the L2 writeback (v54 + leaderinv)
# baseline (speedup 1.0000x reference)
.LBB0_196:
	s_andn2_saveexec_b64 s[10:11], s[10:11]
	s_cbranch_execz .LBB0_217
	buffer_inv sc1
	s_mov_b64 s[10:11], exec
	buffer_wbl2 sc1
	s_waitcnt lgkmcnt(0)
	s_waitcnt vmcnt(0)
	v_mbcnt_lo_u32_b32 v1, s10, 0
	v_mbcnt_hi_u32_b32 v1, s11, v1
	v_cmp_eq_u32_e32 vcc, 0, v1
	s_and_saveexec_b64 s[12:13], vcc
	s_cbranch_execz .LBB0_199
	s_bcnt1_i32_b64 s10, s[10:11]
	v_mov_b32_e32 v2, 0x7000
	v_mov_b32_e32 v3, s10
	global_atomic_add v2, v2, v3, s[6:7] offset:1024 sc0

.LBB0_214:
	s_or_b64 exec, exec, s[6:7]
	s_mov_b64 s[6:7], exec
	v_mbcnt_lo_u32_b32 v0, s6, 0
	v_mbcnt_hi_u32_b32 v0, s7, v0
	v_cmp_eq_u32_e32 vcc, 0, v0
	s_and_saveexec_b64 s[10:11], vcc
	s_cbranch_execz .LBB0_216
	s_bcnt1_i32_b64 s6, s[6:7]
	v_mov_b32_e32 v0, 0x2000
	v_mov_b32_e32 v1, s6
	global_atomic_add v0, v1, s[8:9] offset:1024

.LBB0_265:
	s_andn2_saveexec_b64 s[10:11], s[10:11]
	s_cbranch_execz .LBB0_285
	buffer_inv sc1
	s_waitcnt lgkmcnt(0)
	s_cmp_lg_u32 s99, 0
	s_cbranch_scc1 .Lxcd_local_0
	s_mov_b64 s[12:13], exec
	buffer_wbl2 sc1
	s_waitcnt lgkmcnt(0)
	s_waitcnt vmcnt(0)
	v_mbcnt_lo_u32_b32 v1, s12, 0
	v_mbcnt_hi_u32_b32 v1, s13, v1
	v_cmp_eq_u32_e32 vcc, 0, v1
	s_and_saveexec_b64 s[14:15], vcc
	s_cbranch_execz .LBB0_268
	s_bcnt1_i32_b64 s12, s[12:13]
	v_mov_b32_e32 v2, 0x7000
	v_mov_b32_e32 v3, s12
	global_atomic_add v2, v2, v3, s[6:7] offset:1024 sc0

.Lxcd_local_0:
	s_mov_b64 s[6:7], exec
	v_mbcnt_lo_u32_b32 v0, s6, 0
	v_mbcnt_hi_u32_b32 v0, s7, v0
	v_cmp_eq_u32_e32 vcc, 0, v0
	s_and_saveexec_b64 s[12:13], vcc
	s_cbranch_execz .LBB0_284
	s_bcnt1_i32_b64 s6, s[6:7]
	v_mov_b32_e32 v0, 0x2000
	v_mov_b32_e32 v1, s6
	global_atomic_add v0, v1, s[8:9] offset:1024

.LBB0_644:
	s_andn2_saveexec_b64 s[12:13], s[12:13]
	s_cbranch_execz .LBB0_664
	buffer_inv sc1
	s_waitcnt lgkmcnt(0)
	s_cmp_lg_u32 s99, 0
	s_cbranch_scc1 .Lxcd_local_1
	s_mov_b64 s[12:13], exec
	buffer_wbl2 sc1
	s_waitcnt lgkmcnt(0)
	s_waitcnt vmcnt(0)
	v_mbcnt_lo_u32_b32 v1, s12, 0
	v_mbcnt_hi_u32_b32 v1, s13, v1
	v_cmp_eq_u32_e32 vcc, 0, v1
	s_and_saveexec_b64 s[14:15], vcc
	s_cbranch_execz .LBB0_647
	s_bcnt1_i32_b64 s12, s[12:13]
	v_mov_b32_e32 v2, 0x7000
	v_mov_b32_e32 v3, s12
	global_atomic_add v2, v2, v3, s[8:9] offset:1024 sc0

.Lxcd_local_1:
	s_mov_b64 s[8:9], exec
	v_mbcnt_lo_u32_b32 v0, s8, 0
	v_mbcnt_hi_u32_b32 v0, s9, v0
	v_cmp_eq_u32_e32 vcc, 0, v0
	s_and_saveexec_b64 s[12:13], vcc
	s_cbranch_execz .LBB0_663
	s_bcnt1_i32_b64 s8, s[8:9]
	v_mov_b32_e32 v0, 0x2000
	v_mov_b32_e32 v1, s8
	global_atomic_add v0, v1, s[10:11] offset:1024

.LBB0_1144:
	s_andn2_saveexec_b64 s[12:13], s[12:13]
	s_cbranch_execz .LBB0_1164
	buffer_inv sc1
	s_waitcnt lgkmcnt(0)
	s_cmp_lg_u32 s99, 0
	s_cbranch_scc1 .Lxcd_local_2
	s_mov_b64 s[12:13], exec
	buffer_wbl2 sc1
	s_waitcnt lgkmcnt(0)
	s_waitcnt vmcnt(0)
	v_mbcnt_lo_u32_b32 v1, s12, 0
	v_mbcnt_hi_u32_b32 v1, s13, v1
	v_cmp_eq_u32_e32 vcc, 0, v1
	s_and_saveexec_b64 s[16:17], vcc
	s_cbranch_execz .LBB0_1147
	s_bcnt1_i32_b64 s12, s[12:13]
	v_mov_b32_e32 v2, 0x7000
	v_mov_b32_e32 v3, s12
	global_atomic_add v2, v2, v3, s[8:9] offset:1024 sc0

.LBB0_1310:
	s_andn2_saveexec_b64 s[12:13], s[12:13]
	s_cbranch_execz .LBB0_1330
	buffer_inv sc1
	s_mov_b64 s[12:13], exec
	buffer_wbl2 sc1
	s_waitcnt lgkmcnt(0)
	s_waitcnt vmcnt(0)
	v_mbcnt_lo_u32_b32 v1, s12, 0
	v_mbcnt_hi_u32_b32 v1, s13, v1
	v_cmp_eq_u32_e32 vcc, 0, v1
	s_and_saveexec_b64 s[16:17], vcc
	s_cbranch_execz .LBB0_1313
	s_bcnt1_i32_b64 s12, s[12:13]
	v_mov_b32_e32 v2, 0x7000
	v_mov_b32_e32 v3, s12
	global_atomic_add v2, v2, v3, s[8:9] offset:1024 sc0

.LBB0_1327:
	s_or_b64 exec, exec, s[8:9]
	s_mov_b64 s[8:9], exec
	v_mbcnt_lo_u32_b32 v0, s8, 0
	v_mbcnt_hi_u32_b32 v0, s9, v0
	v_cmp_eq_u32_e32 vcc, 0, v0
	s_and_saveexec_b64 s[12:13], vcc
	s_cbranch_execz .LBB0_1329
	s_bcnt1_i32_b64 s8, s[8:9]
	v_mov_b32_e32 v0, 0x2000
	v_mov_b32_e32 v1, s8
	global_atomic_add v0, v1, s[10:11] offset:1024

.LBB0_1967:
	s_andn2_saveexec_b64 s[12:13], s[12:13]
	s_cbranch_execz .LBB0_1987
	buffer_inv sc1
	s_mov_b64 s[12:13], exec
	buffer_wbl2 sc1
	s_waitcnt lgkmcnt(0)
	s_waitcnt vmcnt(0)
	v_mbcnt_lo_u32_b32 v1, s12, 0
	v_mbcnt_hi_u32_b32 v1, s13, v1
	v_cmp_eq_u32_e32 vcc, 0, v1
	s_and_saveexec_b64 s[14:15], vcc
	s_cbranch_execz .LBB0_1970
	s_bcnt1_i32_b64 s12, s[12:13]
	v_mov_b32_e32 v2, 0x7000
	v_mov_b32_e32 v3, s12
	global_atomic_add v2, v2, v3, s[8:9] offset:1024 sc0
